# P7 epilogue H2 stores: 32 eight-byte stores paired into 16 sixteen-byte write-through stores (v_permlane16_swap), vmcnt counts re-derived
# speedup vs baseline: 1.0204x; 1.0094x over previous
; __device__ __forceinline__ unsigned cvt_pk_bf16(float lo, float hi) { unsigned r; asm volatile("v_cvt_pk_bf16_f32 %0, %1, %2" : "=v"(r) : "v"(lo), "v"(hi)); return r; }
;     __device__ __forceinline__ void fused(f32x4 (&acc)[2][2][4][2], const Unit& u, int wr, int wc, int fr, int fq, PG8_LAS unsigned char* lds, int wid, int lane) const {
;     ...
;         f32x4 ca2[2][2], cb2[2][2];
; #pragma unroll
;         for (int bj = 0; bj < 2; ++bj)
; #pragma unroll
;             for (int n = 0; n < 2; ++n) { ca2[bj][n] = *(const f32x4*)(cv + 1024 + bj * HALF + n * 16); cb2[bj][n] = *(const f32x4*)(cv + 2048 + bj * HALF + n * 16); }
; #pragma unroll
;         for (int ai = 0; ai < 2; ++ai)
; #pragma unroll
;             for (int m = 0; m < 4; ++m) { const int r = ai * HALF + wr * 64 + m * 16 + fr; const f32x2v sr = S[r]; const size_t off = (size_t)(u.pm * BM + r) * ldc + col0;
; #pragma unroll
;                 for (int bj = 0; bj < 2; ++bj)
; #pragma unroll
;                     for (int n = 0; n < 2; ++n) { const f32x4 x1 = acc[ai][bj][m][n]; *(f32x4*)(out + off + bj * HALF + n * 16) = bad1 ? (f32x4){qnan, qnan, qnan, qnan} : x1;
;                         const f32x4 o = (x1 * sr.y) * ca2[bj][n] + cb2[bj][n]; u32x2v w; w.x = cvt_pk_bf16(o[0], o[1]); w.y = cvt_pk_bf16(o[2], o[3]);
;                         if (bad) { w.x = 0x7fc07fc0u; w.y = 0x7fc07fc0u; } *(u32x2v*)(xn + off + bj * HALF + n * 16) = w; }
;                 asm volatile("" ::: "memory"); }
.LBB0_1113:
	s_or_b64 exec, exec, s[0:1]
	v_add_co_u32_e32 v130, vcc, 0x1000, v146
	s_waitcnt lgkmcnt(0)
	s_barrier
	v_mbcnt_lo_u32_b32 v224, -1, 0
	v_mbcnt_hi_u32_b32 v224, -1, v224
	v_bfe_u32 v224, v224, 4, 1
	v_mul_u32_u24_e32 v224, 24, v224
	v_mov_b32_e32 v225, 0
	s_nop 0
	v_addc_co_u32_e32 v131, vcc, 0, v147, vcc
	v_add_co_u32_e32 v134, vcc, 0x2000, v146
	v_or_b32_e32 v167, v183, v1
	s_nop 0
	v_addc_co_u32_e32 v135, vcc, 0, v147, vcc
	global_load_dwordx4 v[154:157], v[134:135], off
	global_load_dwordx4 v[158:161], v[130:131], off
	global_load_dwordx4 v[146:149], v[130:131], off offset:64
	global_load_dwordx4 v[150:153], v[134:135], off offset:64
	global_load_dwordx4 v[138:141], v[134:135], off offset:512
	global_load_dwordx4 v[142:145], v[130:131], off offset:512
	s_waitcnt lgkmcnt(1)
	global_load_dwordx4 v[130:133], v[130:131], off offset:576
	s_nop 0
	global_load_dwordx4 v[134:137], v[134:135], off offset:576
	ds_read_b64 v[200:201], v182 offset:8192
	v_mov_b32_e32 v1, 0x7fc00000
	v_cmp_ne_u32_e32 vcc, 0, v167
	v_lshl_add_u64 v[186:187], v[180:181], 0, v[162:163]
	v_lshl_add_u64 v[198:199], v[178:179], 0, v[162:163]
	v_cndmask_b32_e32 v179, v115, v1, vcc
	v_cndmask_b32_e32 v178, v114, v1, vcc
	s_waitcnt lgkmcnt(0)
	v_pk_mul_f32 v[114:115], v[114:115], v[200:201] op_sel:[0,1]
	v_or_b32_e32 v183, v185, v167
	v_cndmask_b32_e32 v181, v117, v1, vcc
	v_lshl_add_u64 v[202:203], v[186:187], 2, s[18:19]
	v_cndmask_b32_e32 v180, v116, v1, vcc
	v_pk_mul_f32 v[116:117], v[116:117], v[200:201] op_sel:[0,1]
	v_mov_b32_e32 v166, 0x7fc07fc0
	global_store_dwordx4 v[202:203], v[178:181], off sc1
	v_cmp_ne_u32_e64 s[4:5], 0, v183
	v_lshl_add_u64 v[204:205], v[186:187], 1, s[20:21]
	v_cndmask_b32_e32 v187, v121, v1, vcc
	v_cndmask_b32_e32 v186, v120, v1, vcc
	v_cndmask_b32_e32 v185, v119, v1, vcc
	v_cndmask_b32_e32 v184, v118, v1, vcc
	v_pk_mul_f32 v[118:119], v[118:119], v[200:201] op_sel:[0,1]
	v_pk_mul_f32 v[120:121], v[120:121], v[200:201] op_sel:[0,1]
	v_cndmask_b32_e32 v191, v125, v1, vcc
	v_cndmask_b32_e32 v190, v124, v1, vcc
	v_cndmask_b32_e32 v189, v123, v1, vcc
	v_cndmask_b32_e32 v188, v122, v1, vcc
	v_pk_mul_f32 v[122:123], v[122:123], v[200:201] op_sel:[0,1]
	v_pk_mul_f32 v[124:125], v[124:125], v[200:201] op_sel:[0,1]
	v_cndmask_b32_e32 v195, v129, v1, vcc
	v_cndmask_b32_e32 v194, v128, v1, vcc
	v_cndmask_b32_e32 v193, v127, v1, vcc
	v_cndmask_b32_e32 v192, v126, v1, vcc
	v_pk_mul_f32 v[126:127], v[126:127], v[200:201] op_sel:[0,1]
	v_pk_mul_f32 v[128:129], v[128:129], v[200:201] op_sel:[0,1]
	v_lshl_add_u64 v[206:207], v[198:199], 2, s[18:19]
	v_cndmask_b32_e32 v197, v113, v1, vcc
	v_cndmask_b32_e32 v196, v112, v1, vcc
	s_waitcnt vmcnt(7)
	v_pk_fma_f32 v[114:115], v[158:159], v[114:115], v[154:155]
	v_pk_fma_f32 v[116:117], v[160:161], v[116:117], v[156:157]
	v_cvt_pk_bf16_f32 v114, v114, v115
	s_waitcnt vmcnt(5)
	v_pk_fma_f32 v[120:121], v[148:149], v[120:121], v[152:153]
	v_cvt_pk_bf16_f32 v115, v116, v117
	v_cndmask_b32_e64 v208, v114, v166, s[4:5]
	v_cndmask_b32_e64 v209, v115, v166, s[4:5]
	v_pk_fma_f32 v[118:119], v[146:147], v[118:119], v[150:151]
	global_store_dwordx4 v[202:203], v[184:187], off offset:64 sc1
	v_cvt_pk_bf16_f32 v114, v118, v119
	v_cvt_pk_bf16_f32 v115, v120, v121
	s_waitcnt vmcnt(4)
	v_pk_fma_f32 v[124:125], v[144:145], v[124:125], v[140:141]
	v_cndmask_b32_e64 v211, v115, v166, s[4:5]
	v_cndmask_b32_e64 v210, v114, v166, s[4:5]
	v_pk_fma_f32 v[122:123], v[142:143], v[122:123], v[138:139]
	s_nop 1
	v_permlane16_swap_b32 v208, v210
	v_permlane16_swap_b32 v209, v211
	v_lshl_add_u64 v[226:227], v[204:205], 0, v[224:225]
	global_store_dwordx4 v[226:227], v[208:211], off sc1
	global_store_dwordx4 v[202:203], v[188:191], off offset:512 sc1
	v_cvt_pk_bf16_f32 v114, v122, v123
	v_cvt_pk_bf16_f32 v115, v124, v125
	s_waitcnt vmcnt(4)
	v_pk_fma_f32 v[128:129], v[132:133], v[128:129], v[136:137]
	v_cndmask_b32_e64 v213, v115, v166, s[4:5]
	v_cndmask_b32_e64 v212, v114, v166, s[4:5]
	v_pk_fma_f32 v[126:127], v[130:131], v[126:127], v[134:135]
	global_store_dwordx4 v[202:203], v[192:195], off offset:576 sc1
	v_cvt_pk_bf16_f32 v114, v126, v127
	v_cvt_pk_bf16_f32 v115, v128, v129
	v_lshl_add_u64 v[116:117], v[198:199], 1, s[20:21]
	v_cndmask_b32_e64 v215, v115, v166, s[4:5]
	v_cndmask_b32_e64 v214, v114, v166, s[4:5]
	s_nop 1
	v_permlane16_swap_b32 v212, v214
	v_permlane16_swap_b32 v213, v215
	v_lshl_add_u64 v[226:227], v[204:205], 0, v[224:225]
	global_store_dwordx4 v[226:227], v[212:215], off offset:256 sc1
	ds_read_b64 v[114:115], v182 offset:8320
	v_cndmask_b32_e32 v195, v111, v1, vcc
	v_cndmask_b32_e32 v194, v110, v1, vcc
	global_store_dwordx4 v[206:207], v[194:197], off sc1
	s_waitcnt lgkmcnt(0)
; __device__ __forceinline__ unsigned cvt_pk_bf16(float lo, float hi) { unsigned r; asm volatile("v_cvt_pk_bf16_f32 %0, %1, %2" : "=v"(r) : "v"(lo), "v"(hi)); return r; }
;     __device__ __forceinline__ void fused(f32x4 (&acc)[2][2][4][2], const Unit& u, int wr, int wc, int fr, int fq, PG8_LAS unsigned char* lds, int wid, int lane) const {
;     ...
; #pragma unroll
;         for (int ai = 0; ai < 2; ++ai)
; #pragma unroll
;             for (int m = 0; m < 4; ++m) { const int r = ai * HALF + wr * 64 + m * 16 + fr; const f32x2v sr = S[r]; const size_t off = (size_t)(u.pm * BM + r) * ldc + col0;
; #pragma unroll
;                 for (int bj = 0; bj < 2; ++bj)
; #pragma unroll
;                     for (int n = 0; n < 2; ++n) { const f32x4 x1 = acc[ai][bj][m][n]; *(f32x4*)(out + off + bj * HALF + n * 16) = bad1 ? (f32x4){qnan, qnan, qnan, qnan} : x1;
;                         const f32x4 o = (x1 * sr.y) * ca2[bj][n] + cb2[bj][n]; u32x2v w; w.x = cvt_pk_bf16(o[0], o[1]); w.y = cvt_pk_bf16(o[2], o[3]);
;                         if (bad) { w.x = 0x7fc07fc0u; w.y = 0x7fc07fc0u; } *(u32x2v*)(xn + off + bj * HALF + n * 16) = w; }
;                 asm volatile("" ::: "memory"); }
	v_pk_mul_f32 v[110:111], v[110:111], v[114:115] op_sel:[0,1]
	v_pk_mul_f32 v[112:113], v[112:113], v[114:115] op_sel:[0,1]
	v_pk_fma_f32 v[110:111], v[158:159], v[110:111], v[154:155]
	v_pk_fma_f32 v[112:113], v[160:161], v[112:113], v[156:157]
	v_cvt_pk_bf16_f32 v110, v110, v111
	s_nop 0
	v_cvt_pk_bf16_f32 v111, v112, v113
	v_cndmask_b32_e64 v216, v110, v166, s[4:5]
	v_cndmask_b32_e64 v217, v111, v166, s[4:5]
	v_cndmask_b32_e32 v111, v107, v1, vcc
	v_cndmask_b32_e32 v110, v106, v1, vcc
	v_pk_mul_f32 v[106:107], v[106:107], v[114:115] op_sel:[0,1]
	v_cndmask_b32_e32 v113, v109, v1, vcc
	v_cndmask_b32_e32 v112, v108, v1, vcc
	v_pk_mul_f32 v[108:109], v[108:109], v[114:115] op_sel:[0,1]
	v_pk_fma_f32 v[106:107], v[146:147], v[106:107], v[150:151]
	global_store_dwordx4 v[206:207], v[110:113], off offset:64 sc1
	v_pk_fma_f32 v[108:109], v[148:149], v[108:109], v[152:153]
	v_cvt_pk_bf16_f32 v106, v106, v107
	s_nop 0
	v_cvt_pk_bf16_f32 v107, v108, v109
	v_cndmask_b32_e64 v218, v106, v166, s[4:5]
	v_cndmask_b32_e64 v219, v107, v166, s[4:5]
	s_nop 1
	v_permlane16_swap_b32 v216, v218
	v_permlane16_swap_b32 v217, v219
	v_lshl_add_u64 v[226:227], v[116:117], 0, v[224:225]
	global_store_dwordx4 v[226:227], v[216:219], off sc1
	v_cndmask_b32_e32 v107, v103, v1, vcc
	v_cndmask_b32_e32 v106, v102, v1, vcc
	v_pk_mul_f32 v[102:103], v[102:103], v[114:115] op_sel:[0,1]
	v_cndmask_b32_e32 v109, v105, v1, vcc
	v_cndmask_b32_e32 v108, v104, v1, vcc
	v_pk_mul_f32 v[104:105], v[104:105], v[114:115] op_sel:[0,1]
	v_pk_fma_f32 v[102:103], v[142:143], v[102:103], v[138:139]
	global_store_dwordx4 v[206:207], v[106:109], off offset:512 sc1
	v_pk_fma_f32 v[104:105], v[144:145], v[104:105], v[140:141]
	v_cvt_pk_bf16_f32 v102, v102, v103
	s_nop 0
	v_cvt_pk_bf16_f32 v103, v104, v105
	v_cndmask_b32_e64 v220, v102, v166, s[4:5]
	v_cndmask_b32_e64 v221, v103, v166, s[4:5]
	v_cndmask_b32_e32 v103, v99, v1, vcc
	v_cndmask_b32_e32 v102, v98, v1, vcc
	v_pk_mul_f32 v[98:99], v[98:99], v[114:115] op_sel:[0,1]
	v_cndmask_b32_e32 v105, v101, v1, vcc
	v_cndmask_b32_e32 v104, v100, v1, vcc
	v_pk_mul_f32 v[100:101], v[100:101], v[114:115] op_sel:[0,1]
	v_pk_fma_f32 v[98:99], v[130:131], v[98:99], v[134:135]
	global_store_dwordx4 v[206:207], v[102:105], off offset:576 sc1
	v_pk_fma_f32 v[100:101], v[132:133], v[100:101], v[136:137]
	v_cvt_pk_bf16_f32 v98, v98, v99
	s_nop 0
	v_cvt_pk_bf16_f32 v99, v100, v101
	v_cndmask_b32_e64 v222, v98, v166, s[4:5]
	v_cndmask_b32_e64 v223, v99, v166, s[4:5]
	s_nop 1
	v_permlane16_swap_b32 v220, v222
	v_permlane16_swap_b32 v221, v223
	v_lshl_add_u64 v[226:227], v[116:117], 0, v[224:225]
	global_store_dwordx4 v[226:227], v[220:223], off offset:256 sc1
	ds_read_b64 v[102:103], v182 offset:8448
	v_lshl_add_u64 v[104:105], v[176:177], 0, v[162:163]
	v_cndmask_b32_e32 v99, v95, v1, vcc
	v_cndmask_b32_e32 v98, v94, v1, vcc
	v_cndmask_b32_e32 v101, v97, v1, vcc
	s_waitcnt lgkmcnt(0)
	v_pk_mul_f32 v[94:95], v[94:95], v[102:103] op_sel:[0,1]
	v_cndmask_b32_e32 v100, v96, v1, vcc
	v_lshl_add_u64 v[106:107], v[104:105], 2, s[18:19]
	v_pk_mul_f32 v[96:97], v[96:97], v[102:103] op_sel:[0,1]
	v_pk_fma_f32 v[94:95], v[158:159], v[94:95], v[154:155]
	global_store_dwordx4 v[106:107], v[98:101], off sc1
	v_pk_fma_f32 v[96:97], v[160:161], v[96:97], v[156:157]
	v_cvt_pk_bf16_f32 v94, v94, v95
	s_nop 0
	v_cvt_pk_bf16_f32 v95, v96, v97
	v_cndmask_b32_e64 v208, v94, v166, s[4:5]
	v_cndmask_b32_e64 v209, v95, v166, s[4:5]
	v_lshl_add_u64 v[98:99], v[104:105], 1, s[20:21]
	v_cndmask_b32_e32 v95, v91, v1, vcc
	v_cndmask_b32_e32 v94, v90, v1, vcc
	v_pk_mul_f32 v[90:91], v[90:91], v[102:103] op_sel:[0,1]
	v_cndmask_b32_e32 v97, v93, v1, vcc
	v_cndmask_b32_e32 v96, v92, v1, vcc
	v_pk_mul_f32 v[92:93], v[92:93], v[102:103] op_sel:[0,1]
	v_pk_fma_f32 v[90:91], v[146:147], v[90:91], v[150:151]
	global_store_dwordx4 v[106:107], v[94:97], off offset:64 sc1
	v_pk_fma_f32 v[92:93], v[148:149], v[92:93], v[152:153]
	v_cvt_pk_bf16_f32 v90, v90, v91
	s_nop 0
	v_cvt_pk_bf16_f32 v91, v92, v93
	v_cndmask_b32_e64 v210, v90, v166, s[4:5]
	v_cndmask_b32_e64 v211, v91, v166, s[4:5]
	s_nop 1
	v_permlane16_swap_b32 v208, v210
	v_permlane16_swap_b32 v209, v211
	v_lshl_add_u64 v[226:227], v[98:99], 0, v[224:225]
	global_store_dwordx4 v[226:227], v[208:211], off sc1
	v_cndmask_b32_e32 v91, v87, v1, vcc
	v_cndmask_b32_e32 v90, v86, v1, vcc
	v_pk_mul_f32 v[86:87], v[86:87], v[102:103] op_sel:[0,1]
	v_cndmask_b32_e32 v93, v89, v1, vcc
	v_cndmask_b32_e32 v92, v88, v1, vcc
	v_pk_mul_f32 v[88:89], v[88:89], v[102:103] op_sel:[0,1]
	v_pk_fma_f32 v[86:87], v[142:143], v[86:87], v[138:139]
	global_store_dwordx4 v[106:107], v[90:93], off offset:512 sc1
	v_pk_fma_f32 v[88:89], v[144:145], v[88:89], v[140:141]
	v_cvt_pk_bf16_f32 v86, v86, v87
	s_nop 0
	v_cvt_pk_bf16_f32 v87, v88, v89
	v_cndmask_b32_e64 v212, v86, v166, s[4:5]
	v_cndmask_b32_e64 v213, v87, v166, s[4:5]
	v_cndmask_b32_e32 v87, v83, v1, vcc
	v_cndmask_b32_e32 v86, v82, v1, vcc
	v_pk_mul_f32 v[82:83], v[82:83], v[102:103] op_sel:[0,1]
	v_cndmask_b32_e32 v89, v85, v1, vcc
	v_cndmask_b32_e32 v88, v84, v1, vcc
	v_pk_mul_f32 v[84:85], v[84:85], v[102:103] op_sel:[0,1]
	v_pk_fma_f32 v[82:83], v[130:131], v[82:83], v[134:135]
	global_store_dwordx4 v[106:107], v[86:89], off offset:576 sc1
	v_pk_fma_f32 v[84:85], v[132:133], v[84:85], v[136:137]
	v_cvt_pk_bf16_f32 v82, v82, v83
	s_nop 0
	v_cvt_pk_bf16_f32 v83, v84, v85
	v_cndmask_b32_e64 v214, v82, v166, s[4:5]
	v_cndmask_b32_e64 v215, v83, v166, s[4:5]
	s_nop 1
	v_permlane16_swap_b32 v212, v214
	v_permlane16_swap_b32 v213, v215
	v_lshl_add_u64 v[226:227], v[98:99], 0, v[224:225]
	global_store_dwordx4 v[226:227], v[212:215], off offset:256 sc1
	ds_read_b64 v[86:87], v182 offset:8576
	v_lshl_add_u64 v[88:89], v[174:175], 0, v[162:163]
	v_cndmask_b32_e32 v83, v79, v1, vcc
	v_cndmask_b32_e32 v82, v78, v1, vcc
	v_cndmask_b32_e32 v85, v81, v1, vcc
	s_waitcnt lgkmcnt(0)
; __device__ __forceinline__ unsigned cvt_pk_bf16(float lo, float hi) { unsigned r; asm volatile("v_cvt_pk_bf16_f32 %0, %1, %2" : "=v"(r) : "v"(lo), "v"(hi)); return r; }
;     __device__ __forceinline__ void fused(f32x4 (&acc)[2][2][4][2], const Unit& u, int wr, int wc, int fr, int fq, PG8_LAS unsigned char* lds, int wid, int lane) const {
;     ...
; #pragma unroll
;         for (int ai = 0; ai < 2; ++ai)
; #pragma unroll
;             for (int m = 0; m < 4; ++m) { const int r = ai * HALF + wr * 64 + m * 16 + fr; const f32x2v sr = S[r]; const size_t off = (size_t)(u.pm * BM + r) * ldc + col0;
; #pragma unroll
;                 for (int bj = 0; bj < 2; ++bj)
; #pragma unroll
;                     for (int n = 0; n < 2; ++n) { const f32x4 x1 = acc[ai][bj][m][n]; *(f32x4*)(out + off + bj * HALF + n * 16) = bad1 ? (f32x4){qnan, qnan, qnan, qnan} : x1;
;                         const f32x4 o = (x1 * sr.y) * ca2[bj][n] + cb2[bj][n]; u32x2v w; w.x = cvt_pk_bf16(o[0], o[1]); w.y = cvt_pk_bf16(o[2], o[3]);
;                         if (bad) { w.x = 0x7fc07fc0u; w.y = 0x7fc07fc0u; } *(u32x2v*)(xn + off + bj * HALF + n * 16) = w; }
;                 asm volatile("" ::: "memory"); }
	v_pk_mul_f32 v[78:79], v[78:79], v[86:87] op_sel:[0,1]
	v_cndmask_b32_e32 v84, v80, v1, vcc
	v_lshl_add_u64 v[90:91], v[88:89], 2, s[18:19]
	v_pk_mul_f32 v[80:81], v[80:81], v[86:87] op_sel:[0,1]
	v_pk_fma_f32 v[78:79], v[158:159], v[78:79], v[154:155]
	global_store_dwordx4 v[90:91], v[82:85], off sc1
	v_pk_fma_f32 v[80:81], v[160:161], v[80:81], v[156:157]
	v_cvt_pk_bf16_f32 v78, v78, v79
	s_nop 0
	v_cvt_pk_bf16_f32 v79, v80, v81
	v_cndmask_b32_e64 v216, v78, v166, s[4:5]
	v_cndmask_b32_e64 v217, v79, v166, s[4:5]
	v_lshl_add_u64 v[82:83], v[88:89], 1, s[20:21]
	v_cndmask_b32_e32 v79, v75, v1, vcc
	v_cndmask_b32_e32 v78, v74, v1, vcc
	v_pk_mul_f32 v[74:75], v[74:75], v[86:87] op_sel:[0,1]
	v_cndmask_b32_e32 v81, v77, v1, vcc
	v_cndmask_b32_e32 v80, v76, v1, vcc
	v_pk_mul_f32 v[76:77], v[76:77], v[86:87] op_sel:[0,1]
	v_pk_fma_f32 v[74:75], v[146:147], v[74:75], v[150:151]
	global_store_dwordx4 v[90:91], v[78:81], off offset:64 sc1
	v_pk_fma_f32 v[76:77], v[148:149], v[76:77], v[152:153]
	v_cvt_pk_bf16_f32 v74, v74, v75
	s_nop 0
	v_cvt_pk_bf16_f32 v75, v76, v77
	v_cndmask_b32_e64 v218, v74, v166, s[4:5]
	v_cndmask_b32_e64 v219, v75, v166, s[4:5]
	s_nop 1
	v_permlane16_swap_b32 v216, v218
	v_permlane16_swap_b32 v217, v219
	v_lshl_add_u64 v[226:227], v[82:83], 0, v[224:225]
	global_store_dwordx4 v[226:227], v[216:219], off sc1
	v_cndmask_b32_e32 v75, v71, v1, vcc
	v_cndmask_b32_e32 v74, v70, v1, vcc
	v_pk_mul_f32 v[70:71], v[70:71], v[86:87] op_sel:[0,1]
	v_cndmask_b32_e32 v77, v73, v1, vcc
	v_cndmask_b32_e32 v76, v72, v1, vcc
	v_pk_mul_f32 v[72:73], v[72:73], v[86:87] op_sel:[0,1]
	v_pk_fma_f32 v[70:71], v[142:143], v[70:71], v[138:139]
	global_store_dwordx4 v[90:91], v[74:77], off offset:512 sc1
	v_pk_fma_f32 v[72:73], v[144:145], v[72:73], v[140:141]
	v_cvt_pk_bf16_f32 v70, v70, v71
	s_nop 0
	v_cvt_pk_bf16_f32 v71, v72, v73
	v_cndmask_b32_e64 v220, v70, v166, s[4:5]
	v_cndmask_b32_e64 v221, v71, v166, s[4:5]
	v_cndmask_b32_e32 v71, v67, v1, vcc
	v_cndmask_b32_e32 v70, v66, v1, vcc
	v_pk_mul_f32 v[66:67], v[66:67], v[86:87] op_sel:[0,1]
	v_cndmask_b32_e32 v73, v69, v1, vcc
	v_cndmask_b32_e32 v72, v68, v1, vcc
	v_pk_mul_f32 v[68:69], v[68:69], v[86:87] op_sel:[0,1]
	v_pk_fma_f32 v[66:67], v[130:131], v[66:67], v[134:135]
	global_store_dwordx4 v[90:91], v[70:73], off offset:576 sc1
	v_pk_fma_f32 v[68:69], v[132:133], v[68:69], v[136:137]
	v_cvt_pk_bf16_f32 v66, v66, v67
	s_nop 0
	v_cvt_pk_bf16_f32 v67, v68, v69
	v_cndmask_b32_e64 v222, v66, v166, s[4:5]
	v_cndmask_b32_e64 v223, v67, v166, s[4:5]
	s_nop 1
	v_permlane16_swap_b32 v220, v222
	v_permlane16_swap_b32 v221, v223
	v_lshl_add_u64 v[226:227], v[82:83], 0, v[224:225]
	global_store_dwordx4 v[226:227], v[220:223], off offset:256 sc1
	ds_read_b64 v[70:71], v182 offset:9216
	v_lshl_add_u64 v[72:73], v[172:173], 0, v[162:163]
	v_cndmask_b32_e32 v67, v63, v1, vcc
	v_cndmask_b32_e32 v66, v62, v1, vcc
	v_cndmask_b32_e32 v69, v65, v1, vcc
	s_waitcnt lgkmcnt(0)
	v_pk_mul_f32 v[62:63], v[62:63], v[70:71] op_sel:[0,1]
	v_cndmask_b32_e32 v68, v64, v1, vcc
	v_lshl_add_u64 v[74:75], v[72:73], 2, s[18:19]
	v_pk_mul_f32 v[64:65], v[64:65], v[70:71] op_sel:[0,1]
	v_pk_fma_f32 v[62:63], v[158:159], v[62:63], v[154:155]
	global_store_dwordx4 v[74:75], v[66:69], off sc1
	v_pk_fma_f32 v[64:65], v[160:161], v[64:65], v[156:157]
	v_cvt_pk_bf16_f32 v62, v62, v63
	s_nop 0
	v_cvt_pk_bf16_f32 v63, v64, v65
	v_cndmask_b32_e64 v208, v62, v166, s[4:5]
	v_cndmask_b32_e64 v209, v63, v166, s[4:5]
	v_lshl_add_u64 v[66:67], v[72:73], 1, s[20:21]
	v_cndmask_b32_e32 v63, v59, v1, vcc
	v_cndmask_b32_e32 v62, v58, v1, vcc
	v_pk_mul_f32 v[58:59], v[58:59], v[70:71] op_sel:[0,1]
	v_cndmask_b32_e32 v65, v61, v1, vcc
	v_cndmask_b32_e32 v64, v60, v1, vcc
	v_pk_mul_f32 v[60:61], v[60:61], v[70:71] op_sel:[0,1]
	v_pk_fma_f32 v[58:59], v[146:147], v[58:59], v[150:151]
	global_store_dwordx4 v[74:75], v[62:65], off offset:64 sc1
	v_pk_fma_f32 v[60:61], v[148:149], v[60:61], v[152:153]
	v_cvt_pk_bf16_f32 v58, v58, v59
	s_nop 0
	v_cvt_pk_bf16_f32 v59, v60, v61
	v_cndmask_b32_e64 v210, v58, v166, s[4:5]
	v_cndmask_b32_e64 v211, v59, v166, s[4:5]
	s_nop 1
	v_permlane16_swap_b32 v208, v210
	v_permlane16_swap_b32 v209, v211
	v_lshl_add_u64 v[226:227], v[66:67], 0, v[224:225]
	global_store_dwordx4 v[226:227], v[208:211], off sc1
	v_cndmask_b32_e32 v59, v55, v1, vcc
	v_cndmask_b32_e32 v58, v54, v1, vcc
	v_pk_mul_f32 v[54:55], v[54:55], v[70:71] op_sel:[0,1]
	v_cndmask_b32_e32 v61, v57, v1, vcc
	v_cndmask_b32_e32 v60, v56, v1, vcc
	v_pk_mul_f32 v[56:57], v[56:57], v[70:71] op_sel:[0,1]
	v_pk_fma_f32 v[54:55], v[142:143], v[54:55], v[138:139]
	global_store_dwordx4 v[74:75], v[58:61], off offset:512 sc1
	v_pk_fma_f32 v[56:57], v[144:145], v[56:57], v[140:141]
	v_cvt_pk_bf16_f32 v54, v54, v55
	s_nop 0
	v_cvt_pk_bf16_f32 v55, v56, v57
	v_cndmask_b32_e64 v212, v54, v166, s[4:5]
	v_cndmask_b32_e64 v213, v55, v166, s[4:5]
	v_cndmask_b32_e32 v55, v51, v1, vcc
	v_cndmask_b32_e32 v54, v50, v1, vcc
	v_pk_mul_f32 v[50:51], v[50:51], v[70:71] op_sel:[0,1]
	v_cndmask_b32_e32 v57, v53, v1, vcc
	v_cndmask_b32_e32 v56, v52, v1, vcc
	v_pk_mul_f32 v[52:53], v[52:53], v[70:71] op_sel:[0,1]
	v_pk_fma_f32 v[50:51], v[130:131], v[50:51], v[134:135]
	global_store_dwordx4 v[74:75], v[54:57], off offset:576 sc1
	v_pk_fma_f32 v[52:53], v[132:133], v[52:53], v[136:137]
	v_cvt_pk_bf16_f32 v50, v50, v51
	s_nop 0
	v_cvt_pk_bf16_f32 v51, v52, v53
	v_cndmask_b32_e64 v214, v50, v166, s[4:5]
	v_cndmask_b32_e64 v215, v51, v166, s[4:5]
	s_nop 1
	v_permlane16_swap_b32 v212, v214
	v_permlane16_swap_b32 v213, v215
	v_lshl_add_u64 v[226:227], v[66:67], 0, v[224:225]
	global_store_dwordx4 v[226:227], v[212:215], off offset:256 sc1
	ds_read_b64 v[54:55], v182 offset:9344
	v_lshl_add_u64 v[56:57], v[170:171], 0, v[162:163]
	v_cndmask_b32_e32 v51, v47, v1, vcc
	v_cndmask_b32_e32 v50, v46, v1, vcc
	v_cndmask_b32_e32 v53, v49, v1, vcc
	s_waitcnt lgkmcnt(0)
; __device__ __forceinline__ unsigned cvt_pk_bf16(float lo, float hi) { unsigned r; asm volatile("v_cvt_pk_bf16_f32 %0, %1, %2" : "=v"(r) : "v"(lo), "v"(hi)); return r; }
;     __device__ __forceinline__ void fused(f32x4 (&acc)[2][2][4][2], const Unit& u, int wr, int wc, int fr, int fq, PG8_LAS unsigned char* lds, int wid, int lane) const {
;     ...
; #pragma unroll
;         for (int ai = 0; ai < 2; ++ai)
; #pragma unroll
;             for (int m = 0; m < 4; ++m) { const int r = ai * HALF + wr * 64 + m * 16 + fr; const f32x2v sr = S[r]; const size_t off = (size_t)(u.pm * BM + r) * ldc + col0;
; #pragma unroll
;                 for (int bj = 0; bj < 2; ++bj)
; #pragma unroll
;                     for (int n = 0; n < 2; ++n) { const f32x4 x1 = acc[ai][bj][m][n]; *(f32x4*)(out + off + bj * HALF + n * 16) = bad1 ? (f32x4){qnan, qnan, qnan, qnan} : x1;
;                         const f32x4 o = (x1 * sr.y) * ca2[bj][n] + cb2[bj][n]; u32x2v w; w.x = cvt_pk_bf16(o[0], o[1]); w.y = cvt_pk_bf16(o[2], o[3]);
;                         if (bad) { w.x = 0x7fc07fc0u; w.y = 0x7fc07fc0u; } *(u32x2v*)(xn + off + bj * HALF + n * 16) = w; }
;                 asm volatile("" ::: "memory"); }
	v_pk_mul_f32 v[46:47], v[46:47], v[54:55] op_sel:[0,1]
	v_cndmask_b32_e32 v52, v48, v1, vcc
	v_lshl_add_u64 v[58:59], v[56:57], 2, s[18:19]
	v_pk_mul_f32 v[48:49], v[48:49], v[54:55] op_sel:[0,1]
	v_pk_fma_f32 v[46:47], v[158:159], v[46:47], v[154:155]
	global_store_dwordx4 v[58:59], v[50:53], off sc1
	v_pk_fma_f32 v[48:49], v[160:161], v[48:49], v[156:157]
	v_cvt_pk_bf16_f32 v46, v46, v47
	s_nop 0
	v_cvt_pk_bf16_f32 v47, v48, v49
	v_cndmask_b32_e64 v216, v46, v166, s[4:5]
	v_cndmask_b32_e64 v217, v47, v166, s[4:5]
	v_lshl_add_u64 v[50:51], v[56:57], 1, s[20:21]
	v_cndmask_b32_e32 v47, v43, v1, vcc
	v_cndmask_b32_e32 v46, v42, v1, vcc
	v_pk_mul_f32 v[42:43], v[42:43], v[54:55] op_sel:[0,1]
	v_cndmask_b32_e32 v49, v45, v1, vcc
	v_cndmask_b32_e32 v48, v44, v1, vcc
	v_pk_mul_f32 v[44:45], v[44:45], v[54:55] op_sel:[0,1]
	v_pk_fma_f32 v[42:43], v[146:147], v[42:43], v[150:151]
	global_store_dwordx4 v[58:59], v[46:49], off offset:64 sc1
	v_pk_fma_f32 v[44:45], v[148:149], v[44:45], v[152:153]
	v_cvt_pk_bf16_f32 v42, v42, v43
	s_nop 0
	v_cvt_pk_bf16_f32 v43, v44, v45
	v_cndmask_b32_e64 v218, v42, v166, s[4:5]
	v_cndmask_b32_e64 v219, v43, v166, s[4:5]
	s_nop 1
	v_permlane16_swap_b32 v216, v218
	v_permlane16_swap_b32 v217, v219
	v_lshl_add_u64 v[226:227], v[50:51], 0, v[224:225]
	global_store_dwordx4 v[226:227], v[216:219], off sc1
	v_cndmask_b32_e32 v43, v39, v1, vcc
	v_cndmask_b32_e32 v42, v38, v1, vcc
	v_pk_mul_f32 v[38:39], v[38:39], v[54:55] op_sel:[0,1]
	v_cndmask_b32_e32 v45, v41, v1, vcc
	v_cndmask_b32_e32 v44, v40, v1, vcc
	v_pk_mul_f32 v[40:41], v[40:41], v[54:55] op_sel:[0,1]
	v_pk_fma_f32 v[38:39], v[142:143], v[38:39], v[138:139]
	global_store_dwordx4 v[58:59], v[42:45], off offset:512 sc1
	v_pk_fma_f32 v[40:41], v[144:145], v[40:41], v[140:141]
	v_cvt_pk_bf16_f32 v38, v38, v39
	s_nop 0
	v_cvt_pk_bf16_f32 v39, v40, v41
	v_cndmask_b32_e64 v220, v38, v166, s[4:5]
	v_cndmask_b32_e64 v221, v39, v166, s[4:5]
	v_cndmask_b32_e32 v39, v35, v1, vcc
	v_cndmask_b32_e32 v38, v34, v1, vcc
	v_pk_mul_f32 v[34:35], v[34:35], v[54:55] op_sel:[0,1]
	v_cndmask_b32_e32 v41, v37, v1, vcc
	v_cndmask_b32_e32 v40, v36, v1, vcc
	v_pk_mul_f32 v[36:37], v[36:37], v[54:55] op_sel:[0,1]
	v_pk_fma_f32 v[34:35], v[130:131], v[34:35], v[134:135]
	global_store_dwordx4 v[58:59], v[38:41], off offset:576 sc1
	v_pk_fma_f32 v[36:37], v[132:133], v[36:37], v[136:137]
	v_cvt_pk_bf16_f32 v34, v34, v35
	s_nop 0
	v_cvt_pk_bf16_f32 v35, v36, v37
	v_cndmask_b32_e64 v222, v34, v166, s[4:5]
	v_cndmask_b32_e64 v223, v35, v166, s[4:5]
	s_nop 1
	v_permlane16_swap_b32 v220, v222
	v_permlane16_swap_b32 v221, v223
	v_lshl_add_u64 v[226:227], v[50:51], 0, v[224:225]
	global_store_dwordx4 v[226:227], v[220:223], off offset:256 sc1
	ds_read_b64 v[38:39], v182 offset:9472
	v_lshl_add_u64 v[40:41], v[168:169], 0, v[162:163]
	v_cndmask_b32_e32 v35, v31, v1, vcc
	v_cndmask_b32_e32 v34, v30, v1, vcc
	v_cndmask_b32_e32 v37, v33, v1, vcc
	s_waitcnt lgkmcnt(0)
; __device__ __forceinline__ unsigned cvt_pk_bf16(float lo, float hi) { unsigned r; asm volatile("v_cvt_pk_bf16_f32 %0, %1, %2" : "=v"(r) : "v"(lo), "v"(hi)); return r; }
;     __device__ __forceinline__ void fused(f32x4 (&acc)[2][2][4][2], const Unit& u, int wr, int wc, int fr, int fq, PG8_LAS unsigned char* lds, int wid, int lane) const {
;     ...
; #pragma unroll
;         for (int ai = 0; ai < 2; ++ai)
; #pragma unroll
;             for (int m = 0; m < 4; ++m) { const int r = ai * HALF + wr * 64 + m * 16 + fr; const f32x2v sr = S[r]; const size_t off = (size_t)(u.pm * BM + r) * ldc + col0;
; #pragma unroll
;                 for (int bj = 0; bj < 2; ++bj)
; #pragma unroll
;                     for (int n = 0; n < 2; ++n) { const f32x4 x1 = acc[ai][bj][m][n]; *(f32x4*)(out + off + bj * HALF + n * 16) = bad1 ? (f32x4){qnan, qnan, qnan, qnan} : x1;
;                         const f32x4 o = (x1 * sr.y) * ca2[bj][n] + cb2[bj][n]; u32x2v w; w.x = cvt_pk_bf16(o[0], o[1]); w.y = cvt_pk_bf16(o[2], o[3]);
;                         if (bad) { w.x = 0x7fc07fc0u; w.y = 0x7fc07fc0u; } *(u32x2v*)(xn + off + bj * HALF + n * 16) = w; }
;                 asm volatile("" ::: "memory"); }
	v_pk_mul_f32 v[30:31], v[30:31], v[38:39] op_sel:[0,1]
	v_cndmask_b32_e32 v36, v32, v1, vcc
	v_lshl_add_u64 v[42:43], v[40:41], 2, s[18:19]
	v_pk_mul_f32 v[32:33], v[32:33], v[38:39] op_sel:[0,1]
	v_pk_fma_f32 v[30:31], v[158:159], v[30:31], v[154:155]
	global_store_dwordx4 v[42:43], v[34:37], off sc1
	v_pk_fma_f32 v[32:33], v[160:161], v[32:33], v[156:157]
	v_cvt_pk_bf16_f32 v30, v30, v31
	s_nop 0
	v_cvt_pk_bf16_f32 v31, v32, v33
	v_cndmask_b32_e64 v208, v30, v166, s[4:5]
	v_cndmask_b32_e64 v209, v31, v166, s[4:5]
	v_lshl_add_u64 v[34:35], v[40:41], 1, s[20:21]
	v_cndmask_b32_e32 v31, v27, v1, vcc
	v_cndmask_b32_e32 v30, v26, v1, vcc
	v_pk_mul_f32 v[26:27], v[26:27], v[38:39] op_sel:[0,1]
	v_cndmask_b32_e32 v33, v29, v1, vcc
	v_cndmask_b32_e32 v32, v28, v1, vcc
	v_pk_mul_f32 v[28:29], v[28:29], v[38:39] op_sel:[0,1]
	v_pk_fma_f32 v[26:27], v[146:147], v[26:27], v[150:151]
	global_store_dwordx4 v[42:43], v[30:33], off offset:64 sc1
	v_pk_fma_f32 v[28:29], v[148:149], v[28:29], v[152:153]
	v_cvt_pk_bf16_f32 v26, v26, v27
	s_nop 0
	v_cvt_pk_bf16_f32 v27, v28, v29
	v_cndmask_b32_e64 v210, v26, v166, s[4:5]
	v_cndmask_b32_e64 v211, v27, v166, s[4:5]
	s_nop 1
	v_permlane16_swap_b32 v208, v210
	v_permlane16_swap_b32 v209, v211
	v_lshl_add_u64 v[226:227], v[34:35], 0, v[224:225]
	global_store_dwordx4 v[226:227], v[208:211], off sc1
	v_cndmask_b32_e32 v27, v23, v1, vcc
	v_cndmask_b32_e32 v26, v22, v1, vcc
	v_pk_mul_f32 v[22:23], v[22:23], v[38:39] op_sel:[0,1]
	v_cndmask_b32_e32 v29, v25, v1, vcc
	v_cndmask_b32_e32 v28, v24, v1, vcc
	v_pk_mul_f32 v[24:25], v[24:25], v[38:39] op_sel:[0,1]
	v_pk_fma_f32 v[22:23], v[142:143], v[22:23], v[138:139]
	global_store_dwordx4 v[42:43], v[26:29], off offset:512 sc1
	v_pk_fma_f32 v[24:25], v[144:145], v[24:25], v[140:141]
	v_cvt_pk_bf16_f32 v22, v22, v23
	s_nop 0
	v_cvt_pk_bf16_f32 v23, v24, v25
	v_cndmask_b32_e64 v212, v22, v166, s[4:5]
	v_cndmask_b32_e64 v213, v23, v166, s[4:5]
	v_cndmask_b32_e32 v23, v19, v1, vcc
	v_cndmask_b32_e32 v22, v18, v1, vcc
	v_pk_mul_f32 v[18:19], v[18:19], v[38:39] op_sel:[0,1]
	v_cndmask_b32_e32 v25, v21, v1, vcc
	v_cndmask_b32_e32 v24, v20, v1, vcc
	v_pk_mul_f32 v[20:21], v[20:21], v[38:39] op_sel:[0,1]
	v_pk_fma_f32 v[18:19], v[130:131], v[18:19], v[134:135]
	global_store_dwordx4 v[42:43], v[22:25], off offset:576 sc1
	v_pk_fma_f32 v[20:21], v[132:133], v[20:21], v[136:137]
	v_cvt_pk_bf16_f32 v18, v18, v19
	s_nop 0
	v_cvt_pk_bf16_f32 v19, v20, v21
	v_cndmask_b32_e64 v214, v18, v166, s[4:5]
	v_cndmask_b32_e64 v215, v19, v166, s[4:5]
	s_nop 1
	v_permlane16_swap_b32 v212, v214
	v_permlane16_swap_b32 v213, v215
	v_lshl_add_u64 v[226:227], v[34:35], 0, v[224:225]
	global_store_dwordx4 v[226:227], v[212:215], off offset:256 sc1
	ds_read_b64 v[22:23], v182 offset:9600
	v_lshl_add_u64 v[24:25], v[164:165], 0, v[162:163]
	v_cndmask_b32_e32 v19, v15, v1, vcc
	v_cndmask_b32_e32 v18, v14, v1, vcc
	v_cndmask_b32_e32 v21, v17, v1, vcc
	s_waitcnt lgkmcnt(0)
	v_pk_mul_f32 v[14:15], v[14:15], v[22:23] op_sel:[0,1]
	v_cndmask_b32_e32 v20, v16, v1, vcc
	v_lshl_add_u64 v[26:27], v[24:25], 2, s[18:19]
	v_pk_mul_f32 v[16:17], v[16:17], v[22:23] op_sel:[0,1]
	v_pk_fma_f32 v[14:15], v[158:159], v[14:15], v[154:155]
	global_store_dwordx4 v[26:27], v[18:21], off sc1
	v_pk_fma_f32 v[16:17], v[160:161], v[16:17], v[156:157]
	v_cvt_pk_bf16_f32 v14, v14, v15
	s_nop 0
	v_cvt_pk_bf16_f32 v15, v16, v17
	v_cndmask_b32_e64 v216, v14, v166, s[4:5]
	v_cndmask_b32_e64 v217, v15, v166, s[4:5]
	v_lshl_add_u64 v[18:19], v[24:25], 1, s[20:21]
	v_cndmask_b32_e32 v15, v11, v1, vcc
	v_cndmask_b32_e32 v14, v10, v1, vcc
	v_pk_mul_f32 v[10:11], v[10:11], v[22:23] op_sel:[0,1]
	v_cndmask_b32_e32 v17, v13, v1, vcc
	v_cndmask_b32_e32 v16, v12, v1, vcc
	v_pk_mul_f32 v[12:13], v[12:13], v[22:23] op_sel:[0,1]
	v_pk_fma_f32 v[10:11], v[146:147], v[10:11], v[150:151]
	global_store_dwordx4 v[26:27], v[14:17], off offset:64 sc1
	v_pk_fma_f32 v[12:13], v[148:149], v[12:13], v[152:153]
	v_cvt_pk_bf16_f32 v10, v10, v11
	s_nop 0
	v_cvt_pk_bf16_f32 v11, v12, v13
	v_cndmask_b32_e64 v218, v10, v166, s[4:5]
	v_cndmask_b32_e64 v219, v11, v166, s[4:5]
	s_nop 1
	v_permlane16_swap_b32 v216, v218
	v_permlane16_swap_b32 v217, v219
	v_lshl_add_u64 v[226:227], v[18:19], 0, v[224:225]
	global_store_dwordx4 v[226:227], v[216:219], off sc1
	v_cndmask_b32_e32 v11, v7, v1, vcc
	v_cndmask_b32_e32 v10, v6, v1, vcc
	v_pk_mul_f32 v[6:7], v[6:7], v[22:23] op_sel:[0,1]
	v_cndmask_b32_e32 v13, v9, v1, vcc
	v_cndmask_b32_e32 v12, v8, v1, vcc
	v_pk_mul_f32 v[8:9], v[8:9], v[22:23] op_sel:[0,1]
	v_pk_fma_f32 v[6:7], v[142:143], v[6:7], v[138:139]
	global_store_dwordx4 v[26:27], v[10:13], off offset:512 sc1
	v_pk_fma_f32 v[8:9], v[144:145], v[8:9], v[140:141]
	v_cvt_pk_bf16_f32 v6, v6, v7
	s_nop 0
	v_cvt_pk_bf16_f32 v7, v8, v9
	v_cndmask_b32_e64 v220, v6, v166, s[4:5]
	v_cndmask_b32_e64 v221, v7, v166, s[4:5]
	v_cndmask_b32_e32 v7, v3, v1, vcc
	v_cndmask_b32_e32 v6, v2, v1, vcc
	v_pk_mul_f32 v[2:3], v[2:3], v[22:23] op_sel:[0,1]
	v_cndmask_b32_e32 v9, v5, v1, vcc
	v_cndmask_b32_e32 v8, v4, v1, vcc
	v_pk_mul_f32 v[4:5], v[4:5], v[22:23] op_sel:[0,1]
	v_pk_fma_f32 v[2:3], v[130:131], v[2:3], v[134:135]
	global_store_dwordx4 v[26:27], v[6:9], off offset:576 sc1
	v_pk_fma_f32 v[4:5], v[132:133], v[4:5], v[136:137]
	v_cvt_pk_bf16_f32 v1, v2, v3
	s_nop 0
	v_cvt_pk_bf16_f32 v2, v4, v5
	s_nop 0
	v_cndmask_b32_e64 v223, v2, v166, s[4:5]
	v_cndmask_b32_e64 v222, v1, v166, s[4:5]
	s_nop 1
	v_permlane16_swap_b32 v220, v222
	v_permlane16_swap_b32 v221, v223
	v_lshl_add_u64 v[226:227], v[18:19], 0, v[224:225]
	global_store_dwordx4 v[226:227], v[220:223], off offset:256 sc1
